# attention: V-fragment LDS reads for the first two PV k-steps issued in the gaps of the QK MFMA chains (under MFMA time instead of between softmax max and the first PV MFMA)
# baseline (speedup 1.0000x reference)
.LBB0_572:
	s_add_i32 s9, s9, 3
	s_cmp_lt_u32 s83, 4
	s_cselect_b32 s8, s8, s9
	v_lshl_add_u32 v156, s8, 6, v151
	v_cvt_f32_i32_e32 v66, v156
	s_cmp_lt_i32 s8, s84
	v_fma_f32 v81, v117, v66, -v155
	v_add_f32_e32 v97, v149, v81
	v_pk_add_f32 v[66:67], v[190:191], v[80:81] op_sel:[0,1] op_sel_hi:[1,1]
	v_pk_add_f32 v[68:69], v[134:135], v[80:81] op_sel:[0,1] op_sel_hi:[1,1]
	v_pk_add_f32 v[70:71], v[136:137], v[80:81] op_sel:[0,1] op_sel_hi:[1,1]
	v_pk_add_f32 v[72:73], v[138:139], v[80:81] op_sel:[0,1] op_sel_hi:[1,1]
	v_pk_add_f32 v[74:75], v[140:141], v[80:81] op_sel:[0,1] op_sel_hi:[1,1]
	v_pk_add_f32 v[76:77], v[142:143], v[80:81] op_sel:[0,1] op_sel_hi:[1,1]
	v_pk_add_f32 v[78:79], v[144:145], v[80:81] op_sel:[0,1] op_sel_hi:[1,1]
	v_pk_add_f32 v[80:81], v[216:217], v[80:81] op_sel:[0,1] op_sel_hi:[1,1]
	v_pk_add_f32 v[82:83], v[190:191], v[96:97] op_sel:[0,1] op_sel_hi:[1,1]
	v_pk_add_f32 v[84:85], v[134:135], v[96:97] op_sel:[0,1] op_sel_hi:[1,1]
	v_pk_add_f32 v[86:87], v[136:137], v[96:97] op_sel:[0,1] op_sel_hi:[1,1]
	v_pk_add_f32 v[88:89], v[138:139], v[96:97] op_sel:[0,1] op_sel_hi:[1,1]
	v_pk_add_f32 v[90:91], v[140:141], v[96:97] op_sel:[0,1] op_sel_hi:[1,1]
	v_pk_add_f32 v[92:93], v[142:143], v[96:97] op_sel:[0,1] op_sel_hi:[1,1]
	v_pk_add_f32 v[94:95], v[144:145], v[96:97] op_sel:[0,1] op_sel_hi:[1,1]
	v_pk_add_f32 v[96:97], v[216:217], v[96:97] op_sel:[0,1] op_sel_hi:[1,1]
	s_waitcnt lgkmcnt(4)
	v_mfma_f32_32x32x16_bf16 v[66:81], v[192:195], v[98:101], v[66:81]
	v_lshl_add_u32 v188, s81, 14, v152
	ds_read_b64_tr_b16 v[172:173], v188 offset:0
	ds_read_b64_tr_b16 v[174:175], v188 offset:512
	ds_read_b64_tr_b16 v[176:177], v188 offset:4096
	ds_read_b64_tr_b16 v[178:179], v188 offset:4608
	v_mfma_f32_32x32x16_bf16 v[66:81], v[200:203], v[102:105], v[66:81]
	ds_read_b64_tr_b16 v[180:181], v188 offset:8192
	ds_read_b64_tr_b16 v[182:183], v188 offset:8704
	ds_read_b64_tr_b16 v[184:185], v188 offset:12288
	ds_read_b64_tr_b16 v[186:187], v188 offset:12800
	v_mfma_f32_32x32x16_bf16 v[66:81], v[208:211], v[106:109], v[66:81]
	v_mfma_f32_32x32x16_bf16 v[66:81], v[220:223], v[110:113], v[66:81]
	s_waitcnt lgkmcnt(8)
	s_nop 1
	v_mfma_f32_32x32x16_bf16 v[82:97], v[196:199], v[98:101], v[82:97]
	v_mfma_f32_32x32x16_bf16 v[82:97], v[204:207], v[102:105], v[82:97]
	ds_read_b64_tr_b16 v[192:193], v188 offset:1024
	ds_read_b64_tr_b16 v[194:195], v188 offset:1536
	ds_read_b64_tr_b16 v[196:197], v188 offset:5120
	ds_read_b64_tr_b16 v[198:199], v188 offset:5632
	v_mfma_f32_32x32x16_bf16 v[82:97], v[212:215], v[106:109], v[82:97]
	ds_read_b64_tr_b16 v[200:201], v188 offset:9216
	ds_read_b64_tr_b16 v[202:203], v188 offset:9728
	ds_read_b64_tr_b16 v[204:205], v188 offset:13312
	ds_read_b64_tr_b16 v[206:207], v188 offset:13824
	v_mfma_f32_32x32x16_bf16 v[82:97], v[228:231], v[110:113], v[82:97]
	s_cbranch_scc1 .LBB0_574
	s_movk_i32 s36, 0xffe6
	s_movk_i32 s64, 0xffe5
	s_movk_i32 s34, 0xffe7
	v_cmp_lt_i32_e64 s[62:63], s36, v156
	v_cmp_lt_i32_e64 s[64:65], s64, v156
	s_movk_i32 s30, 0xffe8
	v_cmp_lt_i32_e64 s[60:61], s34, v156
	s_and_b64 s[62:63], s[64:65], s[62:63]
	s_movk_i32 s28, 0xffed
	v_cmp_lt_i32_e64 s[58:59], s30, v156
	s_and_b64 s[60:61], s[62:63], s[60:61]
	s_movk_i32 s26, 0xffee
	v_cmp_lt_i32_e64 s[56:57], s28, v156
	s_and_b64 s[58:59], s[60:61], s[58:59]
	s_movk_i32 s24, 0xffef
	v_cmp_lt_i32_e64 s[54:55], s26, v156
	s_and_b64 s[56:57], s[58:59], s[56:57]
	v_cmp_lt_i32_e64 s[52:53], s24, v156
	s_and_b64 s[54:55], s[56:57], s[54:55]
	v_cmp_lt_i32_e64 s[50:51], -16, v156
	s_and_b64 s[52:53], s[54:55], s[52:53]
	v_cmp_lt_i32_e64 s[48:49], -11, v156
	s_and_b64 s[50:51], s[52:53], s[50:51]
	v_cmp_lt_i32_e64 s[46:47], -10, v156
	s_and_b64 s[48:49], s[50:51], s[48:49]
	v_cmp_lt_i32_e64 s[44:45], -9, v156
	s_and_b64 s[46:47], s[48:49], s[46:47]
	s_movk_i32 s10, 0xffe0
	v_cmp_lt_i32_e64 s[42:43], -8, v156
	s_and_b64 s[44:45], s[46:47], s[44:45]
	v_cmp_gt_i32_e64 s[8:9], 1, v156
	v_cmp_lt_i32_e32 vcc, s10, v156
	v_cmp_gt_i32_e64 s[10:11], 0, v156
	v_cmp_lt_i32_e64 s[40:41], -3, v156
	s_and_b64 s[42:43], s[44:45], s[42:43]
	s_or_b64 s[8:9], s[10:11], s[8:9]
	v_cmp_lt_i32_e64 s[38:39], -2, v156
	s_and_b64 s[40:41], s[42:43], s[40:41]
	v_cndmask_b32_e64 v157, v127, v67, s[10:11]
	v_cndmask_b32_e64 v158, v127, v66, s[8:9]
	s_and_b64 s[38:39], s[40:41], s[38:39]
	s_movk_i32 s36, 0xffc6
	v_cndmask_b32_e64 v66, v66, v158, s[38:39]
	v_cndmask_b32_e64 v68, v68, v127, s[38:39]
	v_cndmask_b32_e64 v67, v67, v157, s[38:39]
	s_movk_i32 s38, 0xffc5
	s_movk_i32 s34, 0xffc7
	v_cmp_lt_i32_e64 s[36:37], s36, v156
	v_cmp_lt_i32_e64 s[38:39], s38, v156
	s_movk_i32 s30, 0xffc8
	v_cmp_lt_i32_e64 s[34:35], s34, v156
	s_and_b64 s[36:37], s[38:39], s[36:37]
	s_movk_i32 s28, 0xffcd
	v_cmp_lt_i32_e64 s[30:31], s30, v156
	s_and_b64 s[34:35], s[36:37], s[34:35]
	s_movk_i32 s26, 0xffce
	v_cmp_lt_i32_e64 s[28:29], s28, v156
	s_and_b64 s[30:31], s[34:35], s[30:31]
	s_movk_i32 s24, 0xffcf
	v_cmp_lt_i32_e64 s[26:27], s26, v156
	s_and_b64 s[28:29], s[30:31], s[28:29]
	s_movk_i32 s22, 0xffd0
	v_cmp_lt_i32_e64 s[24:25], s24, v156
	s_and_b64 s[26:27], s[28:29], s[26:27]
	s_movk_i32 s20, 0xffd5
	v_cmp_lt_i32_e64 s[22:23], s22, v156
	s_and_b64 s[24:25], s[26:27], s[24:25]
	s_movk_i32 s18, 0xffd6
	v_cmp_lt_i32_e64 s[20:21], s20, v156
	s_and_b64 s[22:23], s[24:25], s[22:23]
	s_movk_i32 s16, 0xffd7
	v_cmp_lt_i32_e64 s[18:19], s18, v156
	s_and_b64 s[20:21], s[22:23], s[20:21]
	s_movk_i32 s14, 0xffd8
	v_cmp_lt_i32_e64 s[16:17], s16, v156
	s_and_b64 s[18:19], s[20:21], s[18:19]
	s_movk_i32 s12, 0xffdd
	v_cmp_lt_i32_e64 s[14:15], s14, v156
	s_and_b64 s[16:17], s[18:19], s[16:17]
	s_movk_i32 s10, 0xffde
	v_cmp_lt_i32_e64 s[12:13], s12, v156
	s_and_b64 s[14:15], s[16:17], s[14:15]
	s_movk_i32 s8, 0xffdf
	v_cmp_lt_i32_e64 s[10:11], s10, v156
	s_and_b64 s[12:13], s[14:15], s[12:13]
	v_cmp_lt_i32_e64 s[8:9], s8, v156
	s_and_b64 s[10:11], s[12:13], s[10:11]
	s_and_b64 s[8:9], s[10:11], s[8:9]
	s_and_b64 vcc, s[8:9], vcc
	v_cndmask_b32_e64 v81, v81, v127, s[64:65]
	v_cndmask_b32_e64 v80, v80, v127, s[62:63]
	v_cndmask_b32_e64 v79, v79, v127, s[60:61]
	v_cndmask_b32_e64 v78, v78, v127, s[58:59]
	v_cndmask_b32_e64 v77, v77, v127, s[56:57]
	v_cndmask_b32_e64 v76, v76, v127, s[54:55]
	v_cndmask_b32_e64 v75, v75, v127, s[52:53]
	v_cndmask_b32_e64 v74, v74, v127, s[50:51]
	v_cndmask_b32_e64 v73, v73, v127, s[48:49]
	v_cndmask_b32_e64 v72, v72, v127, s[46:47]
	v_cndmask_b32_e64 v71, v71, v127, s[44:45]
	v_cndmask_b32_e64 v70, v70, v127, s[42:43]
	v_cndmask_b32_e64 v69, v69, v127, s[40:41]
	v_cndmask_b32_e64 v97, v97, v127, s[38:39]
	v_cndmask_b32_e64 v96, v96, v127, s[36:37]
	v_cndmask_b32_e64 v95, v95, v127, s[34:35]
	v_cndmask_b32_e64 v94, v94, v127, s[30:31]
	v_cndmask_b32_e64 v93, v93, v127, s[28:29]
	v_cndmask_b32_e64 v92, v92, v127, s[26:27]
	v_cndmask_b32_e64 v91, v91, v127, s[24:25]
	v_cndmask_b32_e64 v90, v90, v127, s[22:23]
	v_cndmask_b32_e64 v89, v89, v127, s[20:21]
	v_cndmask_b32_e64 v88, v88, v127, s[18:19]
	v_cndmask_b32_e64 v87, v87, v127, s[16:17]
	v_cndmask_b32_e64 v86, v86, v127, s[14:15]
	v_cndmask_b32_e64 v85, v85, v127, s[12:13]
	v_cndmask_b32_e64 v84, v84, v127, s[10:11]
	v_cndmask_b32_e64 v83, v83, v127, s[8:9]
	v_cndmask_b32_e32 v82, v82, v127, vcc

.LBB0_576:
	s_andn2_b64 vcc, exec, s[12:13]
	s_cbranch_vccnz .LBB0_582
	v_max_f32_e32 v157, v156, v156
	s_andn2_b64 vcc, exec, s[10:11]
	v_max_f32_e32 v157, 0, v157
	s_cbranch_vccnz .LBB0_581
	v_exp_f32_e64 v158, -v157
	s_and_saveexec_b64 s[10:11], s[4:5]
	ds_write_b32 v147, v158
	s_or_b64 exec, exec, s[10:11]
	v_mul_f32_e32 v154, v154, v158
	ds_read_b128 v[158:161], v114
	ds_read_b128 v[162:165], v114 offset:32
	ds_read_b128 v[166:169], v114 offset:64
	ds_read_b128 v[232:235], v114 offset:96
	s_waitcnt lgkmcnt(3)
	v_pk_mul_f32 v[4:5], v[4:5], v[160:161]
	s_waitcnt lgkmcnt(2)
	v_pk_mul_f32 v[8:9], v[8:9], v[164:165]
	s_waitcnt lgkmcnt(1)
	v_pk_mul_f32 v[12:13], v[12:13], v[168:169]
	s_waitcnt lgkmcnt(0)
	v_pk_mul_f32 v[16:17], v[16:17], v[234:235]
	v_pk_mul_f32 v[14:15], v[14:15], v[232:233]
	v_pk_mul_f32 v[10:11], v[10:11], v[166:167]
	v_pk_mul_f32 v[6:7], v[6:7], v[162:163]
	v_pk_mul_f32 v[2:3], v[2:3], v[158:159]
	v_pk_mul_f32 v[64:65], v[64:65], v[234:235]
	v_pk_mul_f32 v[60:61], v[60:61], v[168:169]
	v_pk_mul_f32 v[56:57], v[56:57], v[164:165]
	v_pk_mul_f32 v[52:53], v[52:53], v[160:161]
	v_pk_mul_f32 v[62:63], v[62:63], v[232:233]
	v_pk_mul_f32 v[58:59], v[58:59], v[166:167]
	v_pk_mul_f32 v[54:55], v[54:55], v[162:163]
	v_pk_mul_f32 v[50:51], v[50:51], v[158:159]
	v_pk_mul_f32 v[48:49], v[48:49], v[234:235]
	v_pk_mul_f32 v[44:45], v[44:45], v[168:169]
	v_pk_mul_f32 v[40:41], v[40:41], v[164:165]
	v_pk_mul_f32 v[36:37], v[36:37], v[160:161]
	v_pk_mul_f32 v[46:47], v[46:47], v[232:233]
	v_pk_mul_f32 v[42:43], v[42:43], v[166:167]
	v_pk_mul_f32 v[38:39], v[38:39], v[162:163]
	v_pk_mul_f32 v[34:35], v[34:35], v[158:159]
	v_pk_mul_f32 v[32:33], v[32:33], v[234:235]
	v_pk_mul_f32 v[28:29], v[28:29], v[168:169]
	v_pk_mul_f32 v[24:25], v[24:25], v[164:165]
	v_pk_mul_f32 v[20:21], v[20:21], v[160:161]
	v_pk_mul_f32 v[30:31], v[30:31], v[232:233]
	v_pk_mul_f32 v[26:27], v[26:27], v[166:167]
	v_pk_mul_f32 v[22:23], v[22:23], v[162:163]
	v_pk_mul_f32 v[18:19], v[18:19], v[158:159]

.LBB0_582:
	v_exp_f32_e32 v66, v66
	v_exp_f32_e32 v67, v67
	v_exp_f32_e32 v68, v68
	v_exp_f32_e32 v69, v69
	v_exp_f32_e32 v70, v70
	v_exp_f32_e32 v71, v71
	v_exp_f32_e32 v72, v72
	v_exp_f32_e32 v73, v73
	v_cvt_pk_bf16_f32 v156, v66, v67
	v_cvt_pk_bf16_f32 v157, v68, v69
	v_cvt_pk_bf16_f32 v158, v70, v71
	v_cvt_pk_bf16_f32 v159, v72, v73
	s_waitcnt lgkmcnt(8)
	s_nop 1
	v_mfma_f32_32x32x16_bf16 v[2:17], v[156:159], v[172:175], v[2:17]
	v_exp_f32_e32 v74, v74
	v_exp_f32_e32 v75, v75
	v_mfma_f32_32x32x16_bf16 v[50:65], v[156:159], v[176:179], v[50:65]
	v_exp_f32_e32 v76, v76
	v_exp_f32_e32 v77, v77
	v_mfma_f32_32x32x16_bf16 v[34:49], v[156:159], v[180:183], v[34:49]
	v_exp_f32_e32 v78, v78
	v_exp_f32_e32 v79, v79
	v_mfma_f32_32x32x16_bf16 v[18:33], v[156:159], v[184:187], v[18:33]
	v_exp_f32_e32 v80, v80
	v_exp_f32_e32 v81, v81
	v_cvt_pk_bf16_f32 v160, v74, v75
	v_cvt_pk_bf16_f32 v161, v76, v77
	v_cvt_pk_bf16_f32 v162, v78, v79
	v_cvt_pk_bf16_f32 v163, v80, v81
	ds_read_b64_tr_b16 v[172:173], v188 offset:2048
	ds_read_b64_tr_b16 v[174:175], v188 offset:2560
	ds_read_b64_tr_b16 v[176:177], v188 offset:6144
	ds_read_b64_tr_b16 v[178:179], v188 offset:6656
	ds_read_b64_tr_b16 v[180:181], v188 offset:10240
	ds_read_b64_tr_b16 v[182:183], v188 offset:10752
	ds_read_b64_tr_b16 v[184:185], v188 offset:14336
	ds_read_b64_tr_b16 v[186:187], v188 offset:14848
	s_waitcnt lgkmcnt(8)
	s_nop 1
	v_mfma_f32_32x32x16_bf16 v[2:17], v[160:163], v[192:195], v[2:17]
	v_exp_f32_e32 v82, v82
	v_exp_f32_e32 v83, v83
	v_mfma_f32_32x32x16_bf16 v[50:65], v[160:163], v[196:199], v[50:65]
	v_exp_f32_e32 v84, v84
	v_exp_f32_e32 v85, v85
	v_mfma_f32_32x32x16_bf16 v[34:49], v[160:163], v[200:203], v[34:49]
	v_exp_f32_e32 v86, v86
	v_exp_f32_e32 v87, v87
	v_mfma_f32_32x32x16_bf16 v[18:33], v[160:163], v[204:207], v[18:33]
	v_exp_f32_e32 v88, v88
	v_exp_f32_e32 v89, v89
	v_cvt_pk_bf16_f32 v164, v82, v83
	v_cvt_pk_bf16_f32 v165, v84, v85
	v_cvt_pk_bf16_f32 v166, v86, v87
	v_cvt_pk_bf16_f32 v167, v88, v89
	ds_read_b64_tr_b16 v[192:193], v188 offset:3072
	ds_read_b64_tr_b16 v[194:195], v188 offset:3584
	ds_read_b64_tr_b16 v[196:197], v188 offset:7168
	ds_read_b64_tr_b16 v[198:199], v188 offset:7680
	ds_read_b64_tr_b16 v[200:201], v188 offset:11264
	ds_read_b64_tr_b16 v[202:203], v188 offset:11776
	ds_read_b64_tr_b16 v[204:205], v188 offset:15360
	ds_read_b64_tr_b16 v[206:207], v188 offset:15872
	s_waitcnt lgkmcnt(8)
	s_nop 1
	v_mfma_f32_32x32x16_bf16 v[2:17], v[164:167], v[172:175], v[2:17]
	v_exp_f32_e32 v90, v90
	v_exp_f32_e32 v91, v91
	v_mfma_f32_32x32x16_bf16 v[50:65], v[164:167], v[176:179], v[50:65]
	v_exp_f32_e32 v92, v92
	v_exp_f32_e32 v93, v93
	v_mfma_f32_32x32x16_bf16 v[34:49], v[164:167], v[180:183], v[34:49]
	v_exp_f32_e32 v94, v94
	v_exp_f32_e32 v95, v95
	v_mfma_f32_32x32x16_bf16 v[18:33], v[164:167], v[184:187], v[18:33]
	v_exp_f32_e32 v96, v96
	v_exp_f32_e32 v97, v97
	v_cvt_pk_bf16_f32 v168, v90, v91
	v_cvt_pk_bf16_f32 v169, v92, v93
	v_cvt_pk_bf16_f32 v170, v94, v95
	v_cvt_pk_bf16_f32 v171, v96, v97
	s_waitcnt lgkmcnt(0)
	s_nop 1
	v_mfma_f32_32x32x16_bf16 v[2:17], v[168:171], v[192:195], v[2:17]
	s_cmp_lt_u32 s83, 3
	v_add_f32_e32 v66, v82, v66
	v_add_f32_e32 v67, v83, v67
	v_add_f32_e32 v66, 0, v66
	v_add_f32_e32 v68, v84, v68
	v_add_f32_e32 v66, v67, v66
	v_add_f32_e32 v69, v85, v69
	v_add_f32_e32 v66, v68, v66
	v_add_f32_e32 v70, v86, v70
	v_mfma_f32_32x32x16_bf16 v[50:65], v[168:171], v[196:199], v[50:65]
	s_cselect_b64 s[8:9], -1, 0
	v_add_f32_e32 v66, v69, v66
	v_add_f32_e32 v71, v87, v71
	v_add_f32_e32 v66, v70, v66
	v_add_f32_e32 v72, v88, v72
	v_add_f32_e32 v66, v71, v66
	v_add_f32_e32 v73, v89, v73
	v_add_f32_e32 v66, v72, v66
	v_add_f32_e32 v74, v90, v74
	v_mfma_f32_32x32x16_bf16 v[34:49], v[168:171], v[200:203], v[34:49]
	s_or_b64 s[0:1], s[8:9], s[0:1]
	v_add_f32_e32 v66, v73, v66
	v_add_f32_e32 v75, v91, v75
	v_add_f32_e32 v66, v74, v66
	v_add_f32_e32 v76, v92, v76
	v_add_f32_e32 v66, v75, v66
	v_add_f32_e32 v77, v93, v77
	v_add_f32_e32 v66, v76, v66
	v_add_f32_e32 v78, v94, v78
	v_mfma_f32_32x32x16_bf16 v[18:33], v[168:171], v[204:207], v[18:33]
	s_and_b64 vcc, exec, s[0:1]
	v_add_f32_e32 v66, v77, v66
	v_add_f32_e32 v79, v95, v79
	v_add_f32_e32 v66, v78, v66
	v_add_f32_e32 v80, v96, v80
	v_add_f32_e32 v66, v79, v66
	v_add_f32_e32 v81, v97, v81
	v_add_f32_e32 v66, v80, v66
	v_add_f32_e32 v66, v81, v66
	v_add_f32_e32 v154, v154, v66
	s_cbranch_vccnz .LBB0_586
	v_cvt_f32_i32_e32 v156, v153
	v_fma_f32 v156, v117, v156, v150
	v_sub_f32_e32 v156, v156, v155
	s_nop 1
	v_max_f32_dpp v156, v156, v156 row_ror:1 row_mask:0xf bank_mask:0xf
	s_nop 1
	v_max_f32_dpp v156, v156, v156 row_ror:2 row_mask:0xf bank_mask:0xf
	s_nop 1
	v_max_f32_dpp v156, v156, v156 row_ror:4 row_mask:0xf bank_mask:0xf
	s_nop 1
	v_max_f32_dpp v156, v156, v156 row_ror:8 row_mask:0xf bank_mask:0xf
	s_nop 1
	v_readlane_b32 s9, v156, 16
	s_and_saveexec_b64 s[0:1], s[6:7]
	s_cbranch_execz .LBB0_585
	s_and_b32 s8, s80, 8
	s_lshl_b32 s8, s8, 2
	s_add_i32 s8, s68, s8
	v_max_f32_e32 v156, s9, v156
	v_mov_b32_e32 v157, s8
	ds_write_b32 v157, v156
